# attention unit prologues: kernarg pointer requested once in front of the queue-pop rendezvous, two serial scalar-load waits removed from the stick-breaking unit prologue
# baseline (speedup 1.0000x reference)
; #define tid (fresh_tid())
; __global__ void __launch_bounds__(512) fwd_megakernel(Args args) {
;     ...
;             for (;;) {
;                 if (tid == 0) *uslot = atomicAdd(qctr, 1u);
;                 __syncthreads();
;                 const unsigned u = *uslot;
.LBB0_392:
	s_load_dwordx2 s[38:39], s[0:1], 0xc8
	v_mov_b32_e32 v0, v156
	s_nop 0
	v_cmp_eq_u32_e32 vcc, 0, v0
	s_and_saveexec_b64 s[4:5], vcc
	s_cbranch_execz .LBB0_394
	v_mov_b64_e32 v[2:3], s[34:35]
	s_cmp_eq_u32 s98, 0
	s_cbranch_scc0 .Lpq_d_have
	global_atomic_add v237, v[2:3], v151, off sc0
	s_mov_b32 s98, 1
	s_waitcnt vmcnt(0)

; #define tid (fresh_tid())
; template <int MODE, int DV> ...
;     ...
;     const int q0 = qb * 256, tw0 = q0 + 32 * wid, t = tw0 + r32;
;     const int NT = 4 * qb + 4;
;     bf16x8 qf[4];
;     { const bf16* qp = QK + (rowbase + t) * 2048 + qcol + hi * 8;
; #pragma unroll
;       for (int ds = 0; ds < 4; ++ds) qf[ds] = *(const GAS bf16x8*)(qp + ds * 16); }
;     float rowc = 0.f;
;     if (MODE == 0) {
;         float sa = 0.f, sb2 = 0.f;
; #pragma unroll
;         for (int ds = 0; ds < 4; ++ds) { const u32x4 w = __builtin_bit_cast(u32x4, qf[ds]);
;             const float e0 = __uint_as_float(w.x << 16), e1 = __uint_as_float(w.x & 0xffff0000u), e2 = __uint_as_float(w.y << 16), e3 = __uint_as_float(w.y & 0xffff0000u);
;             const float e4 = __uint_as_float(w.z << 16), e5 = __uint_as_float(w.z & 0xffff0000u), e6 = __uint_as_float(w.w << 16), e7 = __uint_as_float(w.w & 0xffff0000u);
;             const float q2 = (e0 * e0 + e1 * e1) + (e2 * e2 + e3 * e3) + (e4 * e4 + e5 * e5) + (e6 * e6 + e7 * e7);
;             if (ds < 2) sa += q2; else sb2 += q2; }
;         sa = xhalf_sum(sa); sb2 = xhalf_sum(sb2);
;         rowc = (sqrtf(sa * kinfa) + sqrtf(sb2 * kinfb)) * 1.02f;
;     }
;     const int krow = tid >> 3, kch = tid & 7;
;     const bf16* ksrc = QK + (rowbase + krow) * 2048 + kcol + kch * 8;
;     const unsigned kdst = krow * KSTR + kch * 16;
;     const bf16* vsrc = Vt + (size_t)krow * SEQ + kch * 8;
;     const unsigned vdst = KBUFB + krow * KSTR + kch * 16;
;     const unsigned koff = r32 * KSTR + hi * 16;
;     LAS unsigned* flags = (LAS unsigned*)(lds + FLAG_OFF);
;     f32x16 o[NACC];
; #pragma unroll
;     for (int d = 0; d < NACC; ++d)
; #pragma unroll
;         for (int r = 0; r < 16; ++r) o[d][r] = 0.f;
;     float mrun = 0.f, carry = 0.f, lrun = 0.f;
; __global__ void __launch_bounds__(512) fwd_megakernel(Args args) {
;     ...
;                 const int h = 3 - (int)(u >> 5), qb = 31 - (int)(u & 31), b = (int)(xq >> 1), vh = 2 * h + (int)(xq & 1);
;                 const float slope2 = 1.4426950408889634f * exp2f(-2.0f * (float)(h + 1));
;                 const float kinfa = __uint_as_float(kinfw[(b * 8 + vh) * 2]), kinfb = __uint_as_float(kinfw[(b * 8 + vh) * 2 + 1]);
;                 att::attn_unit<0, 128>(lds, QK, vh * 64, 512 + vh * 64, VtD + ((size_t)(b * 512 + h * 128)) * SEQ, (size_t)b * SEQ, qb, slope2, kinfa, kinfb, F, nullptr, vh * 128);
.LBB0_394:
	s_or_b64 exec, exec, s[4:5]
	s_waitcnt lgkmcnt(0)
	s_barrier
	ds_read_b32 v0, v1 offset:55424
	s_mov_b64 s[4:5], -1
	s_waitcnt lgkmcnt(0)
	s_barrier
	v_cmp_lt_u32_e32 vcc, s67, v0
	v_readfirstlane_b32 s6, v0
	s_cbranch_vccnz .LBB0_391
	s_lshr_b32 s3, s6, 5
	s_sub_i32 s8, 3, s3
	s_sub_i32 s3, 4, s3
	v_cvt_f32_ubyte0_e32 v6, s3
	s_lshl_b32 s4, s8, 1
	v_mul_f32_e32 v0, -2.0, v6
	s_andn2_b32 s56, 31, s6
	s_or_b32 s86, s4, s83
	v_cmp_gt_f32_e32 vcc, s77, v0
	s_and_b64 s[4:5], vcc, exec
	s_cselect_b32 s3, 0xffffffc0, 0
	s_lshl_b32 s4, s86, 3
	s_or_b32 s4, s4, s84
	s_add_u32 s4, s45, s4
	s_addc_u32 s5, s64, 0
	v_mov_b64_e32 v[2:3], s[4:5]
	global_load_dwordx2 v[2:3], v[2:3], off
	s_mov_b64 s[4:5], s[38:39]
	s_mov_b64 s[6:7], s[38:39]
	v_mov_b32_e32 v8, v156
	s_add_u32 s4, s4, 0xf000000
	s_addc_u32 s5, s5, 0
	s_lshl_b32 s8, s8, 21
	s_or_b32 s8, s8, s85
	s_add_u32 s6, s6, s8
	v_readfirstlane_b32 s8, v8
	s_addc_u32 s7, s7, 0
	s_ashr_i32 s87, s8, 6
	s_lshl_b32 s8, s56, 8
	s_lshl_b32 s88, s87, 5
	v_and_b32_e32 v22, 31, v8
	s_add_i32 s88, s88, s8
	v_or_b32_e32 v140, s88, v22
	v_ashrrev_i32_e32 v141, 31, v140
	v_lshl_add_u64 v[4:5], v[140:141], 0, s[36:37]
	v_lshlrev_b64 v[4:5], 12, v[4:5]
	v_bfe_u32 v23, v8, 5, 1
	v_lshl_add_u64 v[4:5], s[4:5], 0, v[4:5]
	s_lshl_b32 s8, s86, 7
	v_lshl_add_u64 v[4:5], v[4:5], 0, s[8:9]
	v_lshlrev_b32_e32 v0, 4, v23
	v_lshl_add_u64 v[4:5], v[4:5], 0, v[0:1]
	global_load_dwordx4 v[112:115], v[4:5], off
	global_load_dwordx4 v[116:119], v[4:5], off offset:32
	global_load_dwordx4 v[120:123], v[4:5], off offset:64
	global_load_dwordx4 v[124:127], v[4:5], off offset:96
	v_cndmask_b32_e32 v7, 0, v158, vcc
	v_fmac_f32_e32 v7, -2.0, v6
	v_exp_f32_e32 v4, v7
	v_and_b32_e32 v141, 63, v8
	v_and_b32_e32 v24, 7, v8
	v_lshlrev_b32_e32 v144, 4, v24
	v_ldexp_f32 v4, v4, s3
	v_mul_f32_e32 v142, 0x3fb8aa3b, v4
	v_ashrrev_i32_e32 v4, 3, v8
	s_lshl_b32 s3, s56, 2
	s_or_b32 s89, s3, 3
	s_or_b32 s3, s3, 2
	v_lshlrev_b32_e32 v160, 3, v23
	v_lshlrev_b32_e32 v150, 3, v24
	v_mad_u32_u24 v163, v22, s79, v0
	v_lshl_add_u32 v164, v24, 2, 0
	v_lshlrev_b32_e32 v165, 2, v23
	v_mov_b32_e32 v0, v1
	s_or_b32 s91, s88, 31
	v_sub_u32_e32 v166, v165, v140
	v_add_u32_e32 v167, 1, v140
	v_mov_b32_e32 v152, v142
	v_mov_b32_e32 v153, v142
	v_mov_b32_e32 v154, v142
	v_mov_b32_e32 v155, v142
	v_mov_b32_e32 v168, 0
	s_mov_b64 s[58:59], 0
	v_mov_b32_e32 v208, v4
	v_ashrrev_i32_e32 v209, 31, v4
	v_lshlrev_b64 v[210:211], 14, v[208:209]
	v_lshl_add_u64 v[210:211], s[6:7], 0, v[210:211]
	v_mad_u64_u32 v[212:213], s[6:7], v4, s79, v[144:145]
	v_lshl_add_u64 v[214:215], v[208:209], 0, s[36:37]
	v_lshlrev_b64 v[214:215], 12, v[214:215]
	v_lshl_add_u64 v[216:217], s[4:5], 0, v[214:215]
	v_lshl_add_u64 v[216:217], v[216:217], 0, s[8:9]
	v_mov_b32_e32 v145, v1
	v_lshl_add_u64 v[146:147], v[216:217], 0, v[144:145]
	v_lshl_add_u64 v[216:217], v[210:211], 0, v[144:145]
	s_lshl_b32 s8, s89, 18
	v_lshl_add_u64 v[148:149], v[216:217], 0, s[10:11]
	v_lshl_add_u64 v[218:219], v[146:147], 0, s[8:9]
	s_lshl_b32 s8, s89, 7
	v_lshl_add_u64 v[220:221], v[148:149], 0, s[8:9]
	v_add_co_u32_e32 v222, vcc, s80, v220
	s_nop 1
	v_addc_co_u32_e32 v223, vcc, 0, v221, vcc
	s_lshl_b32 s8, s3, 18
	global_load_dwordx4 v[196:199], v[218:219], off offset:1024
	global_load_dwordx4 v[200:203], v[220:221], off
	global_load_dwordx4 v[204:207], v[222:223], off
	v_lshl_add_u64 v[224:225], v[146:147], 0, s[8:9]
	s_lshl_b32 s8, s3, 7
	global_load_dwordx4 v[128:131], v[224:225], off offset:1024
	v_lshl_add_u64 v[226:227], v[148:149], 0, s[8:9]
	v_add_co_u32_e32 v228, vcc, s80, v226
	s_nop 1
	v_addc_co_u32_e32 v229, vcc, 0, v227, vcc
	global_load_dwordx4 v[132:135], v[226:227], off
	global_load_dwordx4 v[136:139], v[228:229], off
	s_waitcnt vmcnt(6)
; template <int MODE, int DV> ...
;     ...
;     float rowc = 0.f;
;     if (MODE == 0) {
;         float sa = 0.f, sb2 = 0.f;
; #pragma unroll
;         for (int ds = 0; ds < 4; ++ds) { const u32x4 w = __builtin_bit_cast(u32x4, qf[ds]);
;             const float e0 = __uint_as_float(w.x << 16), e1 = __uint_as_float(w.x & 0xffff0000u), e2 = __uint_as_float(w.y << 16), e3 = __uint_as_float(w.y & 0xffff0000u);
;             const float e4 = __uint_as_float(w.z << 16), e5 = __uint_as_float(w.z & 0xffff0000u), e6 = __uint_as_float(w.w << 16), e7 = __uint_as_float(w.w & 0xffff0000u);
;             const float q2 = (e0 * e0 + e1 * e1) + (e2 * e2 + e3 * e3) + (e4 * e4 + e5 * e5) + (e6 * e6 + e7 * e7);
;             if (ds < 2) sa += q2; else sb2 += q2; }
;         sa = xhalf_sum(sa); sb2 = xhalf_sum(sb2);
;         rowc = (sqrtf(sa * kinfa) + sqrtf(sb2 * kinfb)) * 1.02f;
;     }
;     const int krow = tid >> 3, kch = tid & 7;
;     const bf16* ksrc = QK + (rowbase + krow) * 2048 + kcol + kch * 8;
;     const unsigned kdst = krow * KSTR + kch * 16;
;     const bf16* vsrc = Vt + (size_t)krow * SEQ + kch * 8;
;     const unsigned vdst = KBUFB + krow * KSTR + kch * 16;
;     const unsigned koff = r32 * KSTR + hi * 16;
;     LAS unsigned* flags = (LAS unsigned*)(lds + FLAG_OFF);
;     f32x16 o[NACC];
; #pragma unroll
;     for (int d = 0; d < NACC; ++d)
; #pragma unroll
;         for (int r = 0; r < 16; ++r) o[d][r] = 0.f;
;     float mrun = 0.f, carry = 0.f, lrun = 0.f;
;     bool wdone = false, first = true;
;     bf16x8 ut0, ut1, uone;
;     { const u32x4 c = {0x3F803F80u, 0x3F803F80u, 0x3F803F80u, 0x3F803F80u}; uone = __builtin_bit_cast(bf16x8, c); }
;     if (MODE == 1) {
;         u32x4 a, b;
;         unsigned e0[8], e1[8];
; #pragma unroll
;         for (int j = 0; j < 8; ++j) { const int jj = 8 * (j >> 2) + 4 * hi + (j & 3); e0[j] = (jj > r32) ? 0x3F80u : 0u; e1[j] = (16 + jj > r32) ? 0x3F80u : 0u; }
;         a.x = e0[0] | (e0[1] << 16); a.y = e0[2] | (e0[3] << 16); a.z = e0[4] | (e0[5] << 16); a.w = e0[6] | (e0[7] << 16);
;         b.x = e1[0] | (e1[1] << 16); b.y = e1[2] | (e1[3] << 16); b.z = e1[4] | (e1[5] << 16); b.w = e1[6] | (e1[7] << 16);
;         ut0 = __builtin_bit_cast(bf16x8, a); ut1 = __builtin_bit_cast(bf16x8, b);
;     }
;     u32x4 kreg[2], vreg[2][NVC];
;     ...
;     ATT_LOAD(0, NT - 1); ATT_LOAD(1, (NT - 2 > 0) ? NT - 2 : 0); ATT_STORE(0, 0);
	v_and_b32_e32 v6, 0xffff0000, v112
	v_and_b32_e32 v8, 0xffff0000, v113
	v_and_b32_e32 v14, 0xffff0000, v116
	v_and_b32_e32 v16, 0xffff0000, v117
	v_lshlrev_b32_e32 v5, 16, v112
	v_lshlrev_b32_e32 v7, 16, v113
	v_and_b32_e32 v10, 0xffff0000, v114
	v_lshlrev_b32_e32 v13, 16, v116
	v_lshlrev_b32_e32 v15, 16, v117
	v_and_b32_e32 v18, 0xffff0000, v118
	v_mul_f32_e32 v6, v6, v6
	v_mul_f32_e32 v8, v8, v8
	v_mul_f32_e32 v14, v14, v14
	v_mul_f32_e32 v16, v16, v16
	v_lshlrev_b32_e32 v9, 16, v114
	v_and_b32_e32 v12, 0xffff0000, v115
	v_lshlrev_b32_e32 v17, 16, v118
	v_and_b32_e32 v20, 0xffff0000, v119
	v_mul_f32_e32 v10, v10, v10
	v_mul_f32_e32 v18, v18, v18
	v_fmac_f32_e32 v6, v5, v5
	v_fmac_f32_e32 v8, v7, v7
	v_fmac_f32_e32 v14, v13, v13
	v_fmac_f32_e32 v16, v15, v15
	v_lshlrev_b32_e32 v11, 16, v115
	v_lshlrev_b32_e32 v19, 16, v119
	v_mul_f32_e32 v12, v12, v12
	v_mul_f32_e32 v20, v20, v20
	v_fmac_f32_e32 v10, v9, v9
	v_fmac_f32_e32 v18, v17, v17
	v_add_f32_e32 v5, v6, v8
	v_add_f32_e32 v6, v14, v16
	v_fmac_f32_e32 v12, v11, v11
	v_fmac_f32_e32 v20, v19, v19
	v_add_f32_e32 v5, v10, v5
	v_add_f32_e32 v6, v18, v6
	v_add_f32_e32 v5, v12, v5
	v_add_f32_e32 v6, v20, v6
	v_and_b32_e32 v25, 0xffff0000, v120
	v_and_b32_e32 v27, 0xffff0000, v121
	v_add_f32_e32 v19, v5, v6
	s_nop 0
	v_lshlrev_b32_e32 v21, 16, v120
	v_lshlrev_b32_e32 v26, 16, v121
	v_and_b32_e32 v29, 0xffff0000, v122
	v_mul_f32_e32 v25, v25, v25
	v_mul_f32_e32 v27, v27, v27
	s_nop 0
	v_lshlrev_b32_e32 v28, 16, v122
	v_and_b32_e32 v31, 0xffff0000, v123
	v_and_b32_e32 v33, 0xffff0000, v124
	v_mul_f32_e32 v29, v29, v29
	v_fmac_f32_e32 v25, v21, v21
	v_fmac_f32_e32 v27, v26, v26
	s_nop 0
	s_nop 0
	v_and_b32_e32 v20, 0xffff0000, v125
	v_lshlrev_b32_e32 v30, 16, v123
	v_lshlrev_b32_e32 v32, 16, v124
	v_mul_f32_e32 v31, v31, v31
	v_fmac_f32_e32 v29, v28, v28
	v_add_f32_e32 v7, v25, v27
	v_lshlrev_b32_e32 v17, 16, v125
	v_mul_f32_e32 v28, v33, v33
	v_mul_f32_e32 v20, v20, v20
	v_fmac_f32_e32 v31, v30, v30
	v_add_f32_e32 v7, v29, v7
	v_and_b32_e32 v25, 0xffff0000, v126
	v_fmac_f32_e32 v28, v32, v32
	v_fmac_f32_e32 v20, v17, v17
	v_add_f32_e32 v18, v31, v7
	s_nop 0
	v_lshlrev_b32_e32 v21, 16, v126
	v_add_f32_e32 v17, v28, v20
	v_mul_f32_e32 v20, v25, v25
	s_nop 0
	v_and_b32_e32 v27, 0xffff0000, v127
	v_fmac_f32_e32 v20, v21, v21
	s_nop 0
	v_lshlrev_b32_e32 v26, 16, v127
	v_add_f32_e32 v17, v20, v17
	v_mul_f32_e32 v20, v27, v27
	s_nop 0
	s_nop 0
	v_fmac_f32_e32 v20, v26, v26
	s_nop 0
	s_nop 0
	s_nop 0
	v_add_f32_e32 v17, v20, v17
	s_nop 0
	s_nop 0
	s_nop 0
	v_add_f32_e32 v17, v18, v17
	v_mov_b32_e32 v18, v19
	s_nop 0
	s_nop 0
	v_permlane32_swap_b32_e32 v19, v18
	s_nop 0
	v_add_f32_e32 v18, v19, v18
	s_nop 0
	s_nop 0
	v_mul_f32_e32 v2, v2, v18
	v_mul_f32_e32 v18, 0x4f800000, v2
	v_cmp_gt_f32_e32 vcc, s78, v2
	s_nop 0
	s_nop 0
	s_nop 0
	v_cndmask_b32_e32 v2, v2, v18, vcc
	s_nop 0
	s_nop 0
	s_nop 0
	s_nop 0
	v_sqrt_f32_e32 v26, v2
	s_nop 0
	s_nop 0
	v_add_u32_e32 v18, -1, v26
	v_mov_b32_e32 v25, v17
	v_fma_f32 v19, -v18, v26, v2
	s_nop 0
	v_permlane32_swap_b32_e32 v17, v25
	v_cmp_ge_f32_e64 s[4:5], 0, v19
	v_add_u32_e32 v19, 1, v26
	v_add_f32_e32 v17, v17, v25
	v_fma_f32 v20, -v19, v26, v2
	v_cndmask_b32_e64 v18, v26, v18, s[4:5]
	v_cmp_lt_f32_e64 s[4:5], 0, v20
	v_mul_f32_e32 v3, v3, v17
	v_mul_f32_e32 v17, 0x4f800000, v3
	v_cndmask_b32_e64 v18, v18, v19, s[4:5]
	v_cmp_gt_f32_e64 s[4:5], s78, v3
	v_mul_f32_e32 v19, 0x37800000, v18
	v_cndmask_b32_e32 v18, v18, v19, vcc
	v_cndmask_b32_e64 v3, v3, v17, s[4:5]
	v_sqrt_f32_e32 v17, v3
	v_cmp_class_f32_e32 vcc, v2, v157
	v_add_u32_e32 v162, 0, v212
	s_waitcnt vmcnt(5)
	ds_write_b128 v162, v[196:199]
	s_waitcnt vmcnt(4)
	ds_write_b128 v162, v[200:203] offset:9216
	s_waitcnt vmcnt(3)
	ds_write_b128 v162, v[204:207] offset:18432
	v_cndmask_b32_e32 v2, v18, v2, vcc
	v_add_u32_e32 v18, -1, v17
	v_fma_f32 v19, -v18, v17, v3
	v_cmp_ge_f32_e32 vcc, 0, v19
	v_add_u32_e32 v19, 1, v17
	v_mov_b32_e32 v14, v1
	v_cndmask_b32_e32 v18, v17, v18, vcc
	v_fma_f32 v17, -v19, v17, v3
	v_cmp_lt_f32_e32 vcc, 0, v17
	v_mov_b32_e32 v15, v1
	v_mul_u32_u24_e32 v145, 0x90, v22
	v_cndmask_b32_e32 v17, v18, v19, vcc
	v_mul_f32_e32 v18, 0x37800000, v17
	v_cndmask_b32_e64 v17, v17, v18, s[4:5]
	v_cmp_class_f32_e32 vcc, v3, v157
	s_lshl_b32 s3, s87, 2
	v_mov_b32_e32 v4, v1
	v_cndmask_b32_e32 v3, v17, v3, vcc
	v_add_f32_e32 v2, v2, v3
	v_mul_f32_e32 v161, 0x3f828f5c, v2
	v_mov_b32_e32 v2, v1
	v_mov_b32_e32 v3, v1
	v_mov_b32_e32 v5, v1
	v_mov_b32_e32 v6, v1
	v_mov_b32_e32 v7, v1
	v_mov_b32_e32 v8, v1
	v_mov_b32_e32 v9, v1
	v_mov_b32_e32 v10, v1
	v_mov_b32_e32 v11, v1
	v_mov_b32_e32 v12, v1
	v_mov_b32_e32 v13, v1
	v_mov_b64_e32 v[30:31], v[14:15]
	v_mov_b64_e32 v[46:47], v[14:15]
	v_mov_b64_e32 v[62:63], v[14:15]
	v_mov_b64_e32 v[78:79], v[14:15]
	s_add_i32 s90, s3, 0
	v_cmp_eq_u32_e64 s[4:5], 0, v141
	s_mov_b64 s[6:7], -1
	v_mov_b64_e32 v[28:29], v[12:13]
	v_mov_b64_e32 v[26:27], v[10:11]
	v_mov_b64_e32 v[24:25], v[8:9]
	v_mov_b64_e32 v[22:23], v[6:7]
	v_mov_b64_e32 v[20:21], v[4:5]
	v_mov_b64_e32 v[18:19], v[2:3]
	v_mov_b64_e32 v[16:17], v[0:1]
	v_mov_b64_e32 v[44:45], v[12:13]
	v_mov_b64_e32 v[42:43], v[10:11]
	v_mov_b64_e32 v[40:41], v[8:9]
	v_mov_b64_e32 v[38:39], v[6:7]
	v_mov_b64_e32 v[36:37], v[4:5]
	v_mov_b64_e32 v[34:35], v[2:3]
	v_mov_b64_e32 v[32:33], v[0:1]
	v_mov_b64_e32 v[60:61], v[12:13]
	v_mov_b64_e32 v[58:59], v[10:11]
	v_mov_b64_e32 v[56:57], v[8:9]
	v_mov_b64_e32 v[54:55], v[6:7]
	v_mov_b64_e32 v[52:53], v[4:5]
	v_mov_b64_e32 v[50:51], v[2:3]
	v_mov_b64_e32 v[48:49], v[0:1]
	v_mov_b64_e32 v[76:77], v[12:13]
	v_mov_b64_e32 v[74:75], v[10:11]
	v_mov_b64_e32 v[72:73], v[8:9]
	v_mov_b64_e32 v[70:71], v[6:7]
	v_mov_b64_e32 v[68:69], v[4:5]
	v_mov_b64_e32 v[66:67], v[2:3]
	v_mov_b64_e32 v[64:65], v[0:1]
	v_mov_b32_e32 v14, 0
	s_waitcnt lgkmcnt(0)
	s_barrier
	s_branch .LBB0_399

; #define tid (fresh_tid())
; __global__ void __launch_bounds__(512) fwd_megakernel(Args args) {
;     ...
;             for (;;) {
;                 if (tid == 0) sslot[0] = atomicAdd(qctr, 1u);
;                 __syncthreads();
;                 const unsigned u = sslot[0];
;                 __syncthreads();
;                 if (u >= 1024u) break;
.LBB0_438:
	s_load_dwordx2 s[62:63], s[0:1], 0xc8
	v_mov_b32_e32 v0, v156
	s_nop 0
	v_cmp_eq_u32_e32 vcc, 0, v0
	s_and_saveexec_b64 s[4:5], vcc
	s_cbranch_execz .LBB0_440
	v_mov_b64_e32 v[2:3], s[34:35]
	s_cmp_eq_u32 s98, 0
	s_cbranch_scc0 .Lpq_s_have
	global_atomic_add v238, v[2:3], v125, off sc0
	s_mov_b32 s98, 1
	s_waitcnt vmcnt(0)

; #define LAS __attribute__((address_space(3)))
; template <int MODE, int DV> ...
;     ...
;     const int tid = tid_l, lane = tid & 63, r32 = lane & 31, hi = lane >> 5;
;     const int wid = __builtin_amdgcn_readfirstlane(tid >> 6);
;     const int hsel = wid >> 2;
;     qcol += 64 * hsel; ocol += 64 * hsel;
;     const int q0 = qb * 128, tw0 = q0 + 32 * (wid & 3), t = tw0 + r32;
;     const int NT = 2 * qb + 2;
;     bf16x8 qf[4];
;     { const bf16* qp = QK + (rowbase + t) * 2048 + qcol + hi * 8;
; #pragma unroll
;       for (int ds = 0; ds < 4; ++ds) qf[ds] = *(const GAS bf16x8*)(qp + ds * 16); }
;     float rowc = 0.f;
;     if (MODE == 0) {
;         float sa = 0.f, sb2 = 0.f;
; #pragma unroll
;         for (int ds = 0; ds < 4; ++ds) { const u32x4 w = __builtin_bit_cast(u32x4, qf[ds]);
;             const float e0 = __uint_as_float(w.x << 16), e1 = __uint_as_float(w.x & 0xffff0000u), e2 = __uint_as_float(w.y << 16), e3 = __uint_as_float(w.y & 0xffff0000u);
;             const float e4 = __uint_as_float(w.z << 16), e5 = __uint_as_float(w.z & 0xffff0000u), e6 = __uint_as_float(w.w << 16), e7 = __uint_as_float(w.w & 0xffff0000u);
;             const float q2 = (e0 * e0 + e1 * e1) + (e2 * e2 + e3 * e3) + (e4 * e4 + e5 * e5) + (e6 * e6 + e7 * e7);
;             if (ds < 2) sa += q2; else sb2 += q2; }
;         sa = xhalf_sum(sa); sb2 = xhalf_sum(sb2);
;         rowc = (sqrtf(sa * kinfa) + sqrtf(sb2 * kinfb)) * 1.02f;
;     }
;     const int th = tid >> 8, idx = tid & 255, krow = idx >> 3, kch = idx & 7;
;     const bf16* ksrc = QK + (rowbase + krow) * 2048 + kcol + 64 * th + kch * 8;
;     const unsigned kdst = th * SB2_KB + krow * KSTR + kch * 16;
;     const bf16* vsrc = Vt + (size_t)(64 * th + krow) * SEQ + kch * 8;
;     const unsigned vdst = 2 * SB2_KB + th * SB2_KB + krow * KSTR + kch * 16;
;     const unsigned koff = hsel * SB2_KB + r32 * KSTR + hi * 16;
;     LAS unsigned* flags = flags_;
;     f32x16 o[NACC];
; #pragma unroll
;     for (int d = 0; d < NACC; ++d)
; #pragma unroll
;         for (int r = 0; r < 16; ++r) o[d][r] = 0.f;
;     float mrun = 0.f, carry = 0.f, lrun = 0.f;
;     bool wdone = false, first = true;
;     bf16x8 ut0, ut1, uone;
;     { const u32x4 c = {0x3F803F80u, 0x3F803F80u, 0x3F803F80u, 0x3F803F80u}; uone = __builtin_bit_cast(bf16x8, c); }
;     if (MODE == 1) {
;         u32x4 a, b;
;         unsigned e0[8], e1[8];
; #pragma unroll
.LBB0_440:
	s_or_b64 exec, exec, s[4:5]
	s_waitcnt lgkmcnt(0)
	s_barrier
	ds_read_b32 v0, v134
	s_mov_b64 s[4:5], -1
	s_waitcnt lgkmcnt(0)
	s_barrier
	v_cmp_lt_u32_e32 vcc, s77, v0
	v_readfirstlane_b32 s6, v0
	s_cbranch_vccnz .LBB0_437
	s_lshr_b32 s3, s6, 4
	s_bfe_u32 s8, s6, 0x20002
	s_sub_i32 s3, 63, s3
	v_mov_b32_e32 v4, v156
	s_add_u32 s4, s62, 0xf000000
	s_addc_u32 s5, s63, 0
	s_lshl_b32 s9, s6, 7
	s_and_b32 s83, s9, 0x180
	s_lshl_b32 s9, s8, 23
	s_lshl_b32 s10, s83, 14
	s_or_b32 s9, s9, s10
	s_add_u32 s6, s62, s9
	s_addc_u32 s7, s63, 0
	s_lshl_b32 s84, s8, 13
	v_mov_b32_e32 v123, v1
	v_readfirstlane_b32 s8, v4
	s_ashr_i32 s85, s8, 6
	s_lshl_b32 s9, s85, 5
	s_ashr_i32 s10, s8, 8
	s_lshl_b32 s8, s3, 7
	s_and_b32 s9, s9, 0x60
	v_and_b32_e32 v24, 31, v4
	s_or_b32 s87, s9, s8
	s_lshl_b32 s86, s10, 6
	v_or_b32_e32 v137, s87, v24
	v_or_b32_e32 v0, s84, v137
	s_ashr_i32 s9, s86, 31
	v_lshlrev_b32_e32 v0, 12, v0
	s_add_u32 s8, s83, s86
	v_bfe_u32 v18, v4, 5, 1
	v_lshl_add_u64 v[2:3], s[4:5], 0, v[0:1]
	s_addc_u32 s9, 0, s9
	v_lshl_add_u64 v[2:3], s[8:9], 1, v[2:3]
	v_lshlrev_b32_e32 v0, 4, v18
	v_lshl_add_u64 v[2:3], v[2:3], 0, v[0:1]
	v_ashrrev_i32_e32 v6, 8, v4
	v_bfe_u32 v19, v4, 3, 5
	v_and_b32_e32 v25, 7, v4
	v_and_b32_e32 v136, 63, v4
	global_load_dwordx4 v[66:69], v[2:3], off offset:2048
	global_load_dwordx4 v[70:73], v[2:3], off offset:2080
	global_load_dwordx4 v[74:77], v[2:3], off offset:2112
	global_load_dwordx4 v[78:81], v[2:3], off offset:2144
	v_or_b32_e32 v2, s84, v19
	v_lshlrev_b32_e32 v4, 6, v6
	v_mul_i32_i24_e32 v6, 0x2400, v6
	v_lshlrev_b32_e32 v122, 4, v25
	v_lshlrev_b32_e32 v2, 12, v2
	v_mov_b32_e32 v3, v1
	v_or_b32_e32 v20, v122, v6
	v_or_b32_e32 v6, v4, v19
	v_ashrrev_i32_e32 v7, 31, v6
	v_lshl_add_u64 v[2:3], s[4:5], 0, v[2:3]
	s_lshl_b32 s56, s83, 1
	v_ashrrev_i32_e32 v5, 31, v4
	v_lshlrev_b64 v[6:7], 14, v[6:7]
	v_lshl_add_u64 v[2:3], v[2:3], 0, s[56:57]
	v_lshl_add_u64 v[6:7], s[6:7], 0, v[6:7]
	v_lshl_add_u64 v[2:3], v[4:5], 1, v[2:3]
	s_lshl_b32 s4, s3, 1
	v_lshl_add_u64 v[126:127], v[2:3], 0, v[122:123]
	v_lshl_add_u64 v[2:3], v[6:7], 0, v[122:123]
	s_or_b32 s88, s4, 1
	v_lshl_add_u64 v[128:129], v[2:3], 0, s[58:59]
	s_lshl_b32 s56, s88, 7
	v_lshl_add_u64 v[14:15], v[128:129], 0, s[56:57]
	s_lshl_b32 s56, s88, 18
	v_lshl_add_u64 v[6:7], v[126:127], 0, s[56:57]
	v_add_co_u32_e32 v10, vcc, s79, v6
	global_load_dwordx4 v[2:5], v[14:15], off
	s_nop 0
	v_addc_co_u32_e32 v11, vcc, 0, v7, vcc
	v_add_co_u32_e32 v14, vcc, s80, v14
	v_lshlrev_b32_e32 v139, 2, v18
	s_nop 0
	v_addc_co_u32_e32 v15, vcc, 0, v15, vcc
	v_cmp_gt_u32_e32 vcc, v139, v24
	v_or_b32_e32 v140, 16, v139
	s_lshl_b32 s56, s3, 8
	v_lshlrev_b32_e32 v138, 3, v18
	v_mad_u32_u24 v26, v19, s78, v20
	v_cndmask_b32_e32 v27, 0, v135, vcc
	v_cmp_gt_u32_e32 vcc, v140, v24
	v_lshl_add_u64 v[18:19], v[128:129], 0, s[56:57]
	s_lshl_b32 s56, s3, 19
	v_cndmask_b32_e32 v28, 0, v135, vcc
	v_cmp_lt_u32_e32 vcc, v139, v24
	v_lshl_add_u64 v[20:21], v[126:127], 0, s[56:57]
	global_load_dwordx4 v[6:9], v[6:7], off offset:3072
	s_nop 0
	global_load_dwordx4 v[10:13], v[10:11], off offset:3072
	v_cndmask_b32_e64 v29, 1.0, 0, vcc
	v_add_co_u32_e32 v22, vcc, s79, v20
	global_load_dwordx4 v[14:17], v[14:15], off
	s_nop 0
	v_addc_co_u32_e32 v23, vcc, 0, v21, vcc
	global_load_dwordx4 v[82:85], v[18:19], off
	v_add_co_u32_e32 v18, vcc, s80, v18
	global_load_dwordx4 v[86:89], v[20:21], off offset:3072
	global_load_dwordx4 v[90:93], v[22:23], off offset:3072
	v_addc_co_u32_e32 v19, vcc, 0, v19, vcc
	global_load_dwordx4 v[94:97], v[18:19], off
	v_or_b32_e32 v30, 17, v139
	v_cmp_gt_u32_e32 vcc, v30, v24
	v_or_b32_e32 v142, 2, v139
	v_or_b32_e32 v20, 18, v139
	v_cndmask_b32_e64 v18, 0, 1.0, vcc
	v_cmp_gt_u32_e32 vcc, v142, v24
	v_or_b32_e32 v143, 3, v139
	v_or_b32_e32 v22, 19, v139
	v_cndmask_b32_e32 v19, 0, v135, vcc
	v_cmp_gt_u32_e32 vcc, v20, v24
	v_or_b32_e32 v144, 8, v139
	v_or_b32_e32 v30, 24, v139
	v_cndmask_b32_e32 v20, 0, v135, vcc
	v_cmp_gt_u32_e32 vcc, v143, v24
	v_or_b32_e32 v31, 9, v139
	v_or_b32_e32 v32, 25, v139
	v_cndmask_b32_e64 v21, 0, 1.0, vcc
	v_cmp_gt_u32_e32 vcc, v22, v24
	v_or_b32_e32 v33, 10, v139
	v_or_b32_e32 v34, 26, v139
	v_cndmask_b32_e64 v22, 0, 1.0, vcc
	v_cmp_gt_u32_e32 vcc, v144, v24
	v_or_b32_e32 v35, 11, v139
	v_or_b32_e32 v36, 27, v139
	v_cndmask_b32_e32 v23, 0, v135, vcc
	v_cmp_gt_u32_e32 vcc, v30, v24
	v_add_u32_e32 v145, 0, v26
	v_mul_u32_u24_e32 v123, 0x90, v24
	v_cndmask_b32_e32 v30, 0, v135, vcc
	v_cmp_gt_u32_e32 vcc, v31, v24
	s_mulk_i32 s10, 0x2400
	s_waitcnt vmcnt(0)
	ds_write_b128 v145, v[6:9]
	ds_write_b128 v145, v[2:5] offset:18432
	ds_write_b128 v145, v[10:13] offset:4608
	ds_write_b128 v145, v[14:17] offset:23040
	v_cndmask_b32_e64 v31, 0, 1.0, vcc
	v_cmp_gt_u32_e32 vcc, v32, v24
	v_mov_b32_e32 v14, v1
	v_mov_b32_e32 v15, v1
	v_cndmask_b32_e64 v32, 0, 1.0, vcc
	v_cmp_gt_u32_e32 vcc, v33, v24
	v_lshlrev_b32_e32 v124, 3, v25
	v_or_b32_e32 v98, v29, v27
	v_cndmask_b32_e32 v33, 0, v135, vcc
	v_cmp_gt_u32_e32 vcc, v34, v24
	v_or_b32_e32 v99, v21, v19
	v_or_b32_e32 v100, v31, v23
	v_cndmask_b32_e32 v34, 0, v135, vcc
	v_cmp_gt_u32_e32 vcc, v35, v24
	v_or_b32_e32 v102, v18, v28
	v_or_b32_e32 v103, v22, v20
	v_cndmask_b32_e64 v35, 0, 1.0, vcc
	v_cmp_gt_u32_e32 vcc, v36, v24
	v_or_b32_e32 v101, v35, v33
	v_or_b32_e32 v104, v32, v30
	v_cndmask_b32_e64 v24, 0, 1.0, vcc
	v_or_b32_e32 v105, v24, v34
	v_add3_u32 v146, s10, v123, v0
	v_lshl_add_u32 v147, v25, 2, s81
	v_mov_b32_e32 v0, v1
	v_mov_b32_e32 v2, v1
	v_mov_b32_e32 v3, v1
	v_mov_b32_e32 v4, v1
	v_mov_b32_e32 v5, v1
	v_mov_b32_e32 v6, v1
	v_mov_b32_e32 v7, v1
	v_mov_b32_e32 v8, v1
	v_mov_b32_e32 v9, v1
	v_mov_b32_e32 v10, v1
	v_mov_b32_e32 v11, v1
	v_mov_b32_e32 v12, v1
	v_mov_b32_e32 v13, v1
	v_mov_b64_e32 v[32:33], v[14:15]
	s_lshl_b32 s3, s85, 2
	v_mov_b64_e32 v[30:31], v[12:13]
	v_mov_b64_e32 v[28:29], v[10:11]
	v_mov_b64_e32 v[26:27], v[8:9]
	v_mov_b64_e32 v[24:25], v[6:7]
	v_mov_b64_e32 v[22:23], v[4:5]
	v_mov_b64_e32 v[20:21], v[2:3]
	v_mov_b64_e32 v[18:19], v[0:1]
	v_mov_b64_e32 v[16:17], v[14:15]
	v_or_b32_e32 v141, 1, v139
	s_add_i32 s89, s81, s3
	s_or_b32 s90, s87, 31
	v_or_b32_e32 v148, 32, v139
	v_cmp_eq_u32_e64 s[4:5], 0, v136
	v_mov_b32_e32 v149, 0
	s_mov_b64 s[6:7], 0
	v_mov_b64_e32 v[14:15], v[12:13]
	v_mov_b64_e32 v[12:13], v[10:11]
	v_mov_b64_e32 v[10:11], v[8:9]
	v_mov_b64_e32 v[8:9], v[6:7]
	v_mov_b64_e32 v[6:7], v[4:5]
	v_mov_b64_e32 v[4:5], v[2:3]
	v_mov_b64_e32 v[2:3], v[0:1]
	s_waitcnt lgkmcnt(0)
	s_barrier
	s_branch .LBB0_445
